# v41 + one static s_setprio 1 for waves 0-3 (the older half) during the attention phase, reset at exit
# baseline (speedup 1.0000x reference)
.LBB0_786:
	s_andn2_b64 vcc, exec, s[4:5]
	s_cbranch_vccnz .LBB0_856
	v_readlane_b32 s4, v254, 0
	v_readlane_b32 s5, v254, 1
	s_load_dwordx4 s[36:39], s[4:5], 0xb8
	v_readlane_b32 s4, v253, 32
	v_readlane_b32 s5, v253, 33
	s_mov_b32 s7, s5
	v_readlane_b32 s4, v253, 36
	s_waitcnt lgkmcnt(0)
	s_add_u32 s62, s36, 0x3cb2000
	s_addc_u32 s63, s37, 0
	s_add_u32 s70, s38, 0x11139000
	s_addc_u32 s71, s39, 0
	s_add_u32 s88, s38, 0x131b9000
	s_addc_u32 s89, s39, 0
	s_add_u32 s54, s38, 0x8f21000
	s_addc_u32 s55, s39, 0
	v_readlane_b32 s5, v253, 37
	s_add_u32 s44, s38, 0xf0b1000
	s_mov_b32 s5, s7
	s_addc_u32 s45, s39, 0
	s_lshl_b32 s6, s4, 4
	v_writelane_b32 v253, s4, 32
	v_mov_b32_e32 v127, v192
	v_mov_b32_e32 v125, v173
	v_writelane_b32 v253, s5, 33
	s_lshl_b64 s[4:5], s[6:7], 2
	s_add_u32 s4, s38, s4
	v_ashrrev_i32_e32 v122, 3, v127
	s_addc_u32 s5, s39, s5
	v_max_i32_e32 v0, 48, v122
	v_writelane_b32 v253, s4, 38
	v_readfirstlane_b32 s0, v127
	v_subrev_u32_e32 v124, 48, v0
	v_lshlrev_b32_e32 v0, 3, v127
	v_and_b32_e32 v154, 63, v127
	v_writelane_b32 v253, s5, 39
	v_bfe_u32 v1, v127, 4, 2
	s_ashr_i32 s0, s0, 1
	v_and_b32_e32 v172, 48, v127
	v_and_b32_e32 v126, 56, v0
	s_movk_i32 s4, 0x48
	v_and_b32_e32 v155, 15, v127
	s_and_b32 s85, s0, 0xffffffe0
	v_lshlrev_b32_e32 v157, 3, v1
	v_lshl_add_u64 v[120:121], s[54:55], 0, v[172:173]
	v_max_u32_e32 v0, 48, v126
	v_max_u32_e32 v2, 48, v154
	v_mul_lo_u32 v3, v122, s4
	v_lshlrev_b32_e32 v158, 2, v1
	v_lshlrev_b32_e32 v1, 2, v154
	v_lshlrev_b32_e32 v172, 1, v126
	v_cmp_eq_u32_e32 vcc, 0, v127
	v_or_b32_e32 v156, s85, v155
	v_ashrrev_i32_e32 v123, 31, v122
	v_cmp_gt_i32_e64 s[4:5], 64, v127
	s_or_b32 s93, s0, 31
	v_mul_u32_u24_e32 v159, 0x48, v155
	v_xor_b32_e32 v160, 64, v1
	v_xor_b32_e32 v161, 0x80, v1
	v_lshl_add_u64 v[128:129], s[70:71], 0, v[172:173]
	v_sub_u32_e32 v162, 0, v157
	s_mov_b64 s[66:67], 0
	v_lshlrev_b32_e32 v130, 1, v0
	v_lshlrev_b32_e32 v132, 2, v2
	v_lshlrev_b32_e32 v163, 1, v3
	v_mov_b32_e32 v235, 0
	v_readfirstlane_b32 s100, v192
	s_nop 3
	s_lshr_b32 s100, s100, 6
	s_cmp_ge_u32 s100, 4
	s_cbranch_scc1 .Lattn_prio_done
	s_setprio 1
